# fixup_rows loop: the store-drain wait before the next iteration's address arithmetic dropped (WAR only); stacked on the ERES / PRO de-serialisations
# speedup vs baseline: 1.0073x; 1.0073x over previous
.LBB0_156:
	s_mov_b32 s2, 0x2e8ba2e9
	v_mul_hi_i32 v2, v15, s2
	v_lshrrev_b32_e32 v3, 31, v2
	v_ashrrev_i32_e32 v2, 7, v2
	v_add_u32_e32 v4, v2, v3
	v_mov_b64_e32 v[2:3], s[28:29]
	v_mad_i64_i32 v[2:3], s[16:17], v4, s12, v[2:3]
	s_mov_b64 s[16:17], 0x200
	s_nop 0
	v_cmp_gt_i64_e32 vcc, s[16:17], v[2:3]
	s_and_saveexec_b64 s[88:89], vcc
	s_cbranch_execz .LBB0_162
	v_ashrrev_i32_e32 v3, 31, v2
	v_lshrrev_b32_e32 v3, 29, v3
	v_add_u32_e32 v3, v2, v3
	v_and_b32_e32 v5, -8, v3
	v_sub_u32_e32 v5, v2, v5
	v_cmp_lt_i32_e32 vcc, -1, v5
	s_and_saveexec_b64 s[16:17], vcc
	s_xor_b64 s[90:91], exec, s[16:17]
	v_lshlrev_b32_e32 v2, 6, v5
	s_andn2_saveexec_b64 s[90:91], s[90:91]
	v_lshl_add_u32 v2, v5, 6, v5
	s_or_b64 exec, exec, s[90:91]
	v_ashrrev_i32_e32 v3, 3, v3
	v_add_u32_e32 v2, v2, v3
	v_ashrrev_i32_e32 v3, 31, v2
	v_lshrrev_b32_e32 v3, 27, v3
	v_add_u32_e32 v3, v2, v3
	v_ashrrev_i32_e32 v5, 5, v3
	v_lshlrev_b32_e32 v5, 3, v5
	s_nop 0
	v_sub_u32_e32 v6, 0x80, v5
	v_min_i32_e32 v6, 8, v6
	v_sub_u32_e32 v7, 0, v6
	v_max_i32_e32 v6, v6, v7
	v_cvt_f32_u32_e32 v7, v6
	v_and_b32_e32 v3, 0xffffffe0, v3
	v_sub_u32_e32 v2, v2, v3
	v_sub_u32_e32 v8, 0, v2
	v_rcp_iflag_f32_e32 v7, v7
	v_ashrrev_i32_e32 v3, 31, v2
	v_max_i32_e32 v2, v2, v8
	v_sub_u32_e32 v8, 0, v6
	v_mul_f32_e32 v7, 0x4f7ffffe, v7
	v_cvt_u32_f32_e32 v7, v7
	v_mul_lo_u32 v8, v8, v7
	v_mul_hi_u32 v8, v7, v8
	v_add_u32_e32 v7, v7, v8
	v_mul_hi_u32 v7, v2, v7
	v_mul_lo_u32 v7, v7, v6
	v_sub_u32_e32 v2, v2, v7
	v_sub_u32_e32 v7, v2, v6
	v_cmp_ge_u32_e32 vcc, v2, v6
	s_nop 1
	v_cndmask_b32_e32 v2, v2, v7, vcc
	v_sub_u32_e32 v7, v2, v6
	v_cmp_ge_u32_e32 vcc, v2, v6
	s_nop 1
	v_cndmask_b32_e32 v2, v2, v7, vcc
	v_xor_b32_e32 v2, v2, v3
	v_sub_u32_e32 v2, v2, v3
	v_add_u32_e32 v16, v5, v2
